# added nt hints on PEER LN2-stage out loads/stores (on top of P3 preload, V-pass lns readlane, lane-permuted coalesced residual, nt on V streaming accesses)
# speedup vs baseline: 1.0270x; 1.0003x over previous
.LBB0_938:
	s_waitcnt vmcnt(19)
	v_lshlrev_b64 v[0:1], 13, v[176:177]
	s_waitcnt vmcnt(9)
	v_lshl_add_u64 v[40:41], v[172:173], 0, v[0:1]
	global_load_dwordx4 v[0:3], v[152:153], off
	global_load_dwordx4 v[4:7], v[152:153], off offset:1024
	global_load_dwordx4 v[8:11], v[154:155], off
	global_load_dwordx4 v[12:15], v[154:155], off offset:1024
	global_load_dwordx4 v[64:67], v[40:41], off nt
	global_load_dwordx4 v[68:71], v[40:41], off offset:1024 nt
	global_load_dwordx4 v[16:19], v[152:153], off offset:2048
	global_load_dwordx4 v[20:23], v[152:153], off offset:3072
	global_load_dwordx4 v[24:27], v[154:155], off offset:2048
	global_load_dwordx4 v[28:31], v[154:155], off offset:3072
	global_load_dwordx4 v[76:79], v[40:41], off offset:2048 nt
	global_load_dwordx4 v[80:83], v[40:41], off offset:3072 nt
	global_load_dwordx4 v[32:35], v[156:157], off
	global_load_dwordx4 v[36:39], v[158:159], off
	v_add_co_u32_e32 v72, vcc, s41, v40
	s_mov_b32 s0, 0
	s_nop 0
	v_addc_co_u32_e32 v73, vcc, 0, v41, vcc
	global_load_dwordx4 v[40:43], v[160:161], off
	global_load_dwordx4 v[44:47], v[162:163], off
	global_load_dwordx4 v[104:107], v[72:73], off nt
	global_load_dwordx4 v[112:115], v[72:73], off offset:1024 nt
	global_load_dwordx4 v[48:51], v[164:165], off
	global_load_dwordx4 v[52:55], v[166:167], off
	global_load_dwordx4 v[56:59], v[168:169], off
	global_load_dwordx4 v[60:63], v[170:171], off
	global_load_dwordx4 v[120:123], v[72:73], off offset:2048 nt
	global_load_dwordx4 v[124:127], v[72:73], off offset:3072 nt
	s_branch .LBB0_940
.LBB0_939:
	v_mov_b32_e32 v130, v69
	v_mov_b32_e32 v131, v65
	v_mov_b32_e32 v132, v68
	v_mov_b32_e32 v133, v64
	v_pk_add_f32 v[130:131], v[130:131], v[132:133]
	v_mov_b32_e32 v132, v71
	v_mov_b32_e32 v133, v67
	v_mov_b32_e32 v134, v70
	v_mov_b32_e32 v135, v66
	v_pk_add_f32 v[132:133], v[132:133], v[134:135]
	v_mov_b32_e32 v134, v78
	v_pk_add_f32 v[130:131], v[132:133], v[130:131]
	v_mov_b32_e32 v132, v79
	v_mov_b32_e32 v133, v77
	v_mov_b32_e32 v135, v76
	v_pk_add_f32 v[132:133], v[132:133], v[134:135]
	v_add_f32_e32 v131, 0, v131
	v_pk_add_f32 v[132:133], v[132:133], v[132:133] op_sel_hi:[0,1]
	v_pk_add_f32 v[134:135], v[80:81], v[80:81] op_sel_hi:[1,0]
	v_pk_add_f32 v[176:177], v[82:83], v[82:83] op_sel_hi:[1,0]
	v_add_f32_e32 v131, v130, v131
	v_mov_b32_e32 v132, v105
	v_mov_b32_e32 v130, v104
	v_mov_b32_e32 v176, v107
	v_mov_b32_e32 v134, v106
	v_pk_add_f32 v[130:131], v[132:133], v[130:131]
	v_pk_add_f32 v[132:133], v[176:177], v[134:135]
	v_mov_b32_e32 v134, v114
	v_pk_add_f32 v[130:131], v[132:133], v[130:131]
	v_mov_b32_e32 v132, v115
	v_mov_b32_e32 v133, v113
	v_mov_b32_e32 v135, v112
	v_pk_add_f32 v[132:133], v[132:133], v[134:135]
	v_pk_add_f32 v[130:131], v[130:131], v[130:131] op_sel_hi:[0,1]
	v_pk_add_f32 v[132:133], v[132:133], v[132:133] op_sel_hi:[0,1]
	v_pk_add_f32 v[134:135], v[120:121], v[120:121] op_sel_hi:[1,0]
	v_pk_add_f32 v[176:177], v[122:123], v[122:123] op_sel_hi:[1,0]
	v_mov_b32_e32 v132, v125
	v_mov_b32_e32 v130, v124
	v_mov_b32_e32 v176, v127
	v_mov_b32_e32 v134, v126
	v_pk_add_f32 v[130:131], v[132:133], v[130:131]
	v_pk_add_f32 v[132:133], v[176:177], v[134:135]
	v_lshl_add_u64 v[128:129], v[128:129], 0, v[138:139]
	v_pk_add_f32 v[130:131], v[132:133], v[130:131]
	s_add_i32 s0, s0, 1
	v_add_f32_e32 v130, v130, v131
	ds_bpermute_b32 v131, v204, v130
	s_cmp_eq_u32 s0, 16
	s_waitcnt lgkmcnt(0)
	v_add_f32_e32 v130, v130, v131
	ds_bpermute_b32 v131, v205, v130
	s_waitcnt lgkmcnt(0)
	v_add_f32_e32 v130, v130, v131
	ds_bpermute_b32 v131, v206, v130
	s_waitcnt lgkmcnt(0)
	v_add_f32_e32 v130, v130, v131
	ds_bpermute_b32 v131, v201, v130
	s_waitcnt lgkmcnt(0)
	v_add_f32_e32 v130, v130, v131
	ds_bpermute_b32 v131, v202, v130
	s_waitcnt lgkmcnt(0)
	v_add_f32_e32 v130, v130, v131
	ds_bpermute_b32 v131, v203, v130
	s_waitcnt lgkmcnt(0)
	v_add_f32_e32 v130, v130, v131
	v_mul_f32_e32 v130, 0x3a000000, v130
	v_pk_add_f32 v[64:65], v[64:65], v[130:131] op_sel_hi:[1,0] neg_lo:[0,1] neg_hi:[0,1]
	v_pk_add_f32 v[68:69], v[68:69], v[130:131] op_sel_hi:[1,0] neg_lo:[0,1] neg_hi:[0,1]
	v_pk_mul_f32 v[132:133], v[64:65], v[64:65]
	v_pk_add_f32 v[66:67], v[66:67], v[130:131] op_sel_hi:[1,0] neg_lo:[0,1] neg_hi:[0,1]
	v_pk_mul_f32 v[176:177], v[68:69], v[68:69]
	v_pk_add_f32 v[70:71], v[70:71], v[130:131] op_sel_hi:[1,0] neg_lo:[0,1] neg_hi:[0,1]
	v_pk_add_f32 v[76:77], v[76:77], v[130:131] op_sel_hi:[1,0] neg_lo:[0,1] neg_hi:[0,1]
	v_pk_mul_f32 v[134:135], v[66:67], v[66:67]
	v_pk_mul_f32 v[178:179], v[70:71], v[70:71]
	v_pk_mul_f32 v[180:181], v[76:77], v[76:77]
	v_pk_add_f32 v[78:79], v[78:79], v[130:131] op_sel_hi:[1,0] neg_lo:[0,1] neg_hi:[0,1]
	v_add_f32_e32 v176, v176, v177
	v_add_f32_e32 v132, v132, v133
	v_pk_mul_f32 v[182:183], v[78:79], v[78:79]
	v_pk_add_f32 v[104:105], v[104:105], v[130:131] op_sel_hi:[1,0] neg_lo:[0,1] neg_hi:[0,1]
	v_pk_add_f32 v[112:113], v[112:113], v[130:131] op_sel_hi:[1,0] neg_lo:[0,1] neg_hi:[0,1]
	v_add_f32_e32 v176, v178, v176
	v_add_f32_e32 v132, v134, v132
	v_add_f32_e32 v133, v180, v181
	v_pk_add_f32 v[80:81], v[80:81], v[130:131] op_sel_hi:[1,0] neg_lo:[0,1] neg_hi:[0,1]
	v_mov_b32_e32 v212, v113
	v_mov_b32_e32 v213, v105
	v_add_f32_e32 v176, v179, v176
	v_add_f32_e32 v132, v135, v132
	v_add_f32_e32 v133, v182, v133
	v_pk_mul_f32 v[184:185], v[80:81], v[80:81]
	v_pk_add_f32 v[82:83], v[82:83], v[130:131] op_sel_hi:[1,0] neg_lo:[0,1] neg_hi:[0,1]
	v_pk_add_f32 v[106:107], v[106:107], v[130:131] op_sel_hi:[1,0] neg_lo:[0,1] neg_hi:[0,1]
	v_pk_add_f32 v[114:115], v[114:115], v[130:131] op_sel_hi:[1,0] neg_lo:[0,1] neg_hi:[0,1]
	v_mov_b32_e32 v210, v112
	v_mov_b32_e32 v211, v104
	v_pk_mul_f32 v[212:213], v[212:213], v[212:213]
	v_add_f32_e32 v132, v132, v176
	v_add_f32_e32 v133, v183, v133
	v_pk_mul_f32 v[186:187], v[82:83], v[82:83]
	v_pk_fma_f32 v[210:211], v[210:211], v[210:211], v[212:213]
	v_mov_b32_e32 v212, v114
	v_mov_b32_e32 v213, v106
	v_pk_add_f32 v[120:121], v[120:121], v[130:131] op_sel_hi:[1,0] neg_lo:[0,1] neg_hi:[0,1]
	v_pk_add_f32 v[124:125], v[124:125], v[130:131] op_sel_hi:[1,0] neg_lo:[0,1] neg_hi:[0,1]
	v_add_f32_e32 v132, v133, v132
	v_add_f32_e32 v133, v184, v185
	v_pk_fma_f32 v[210:211], v[212:213], v[212:213], v[210:211]
	v_mov_b32_e32 v212, v125
	v_mov_b32_e32 v213, v121
	v_add_f32_e32 v133, v186, v133
	v_mov_b32_e32 v214, v115
	v_mov_b32_e32 v215, v107
	v_pk_add_f32 v[122:123], v[122:123], v[130:131] op_sel_hi:[1,0] neg_lo:[0,1] neg_hi:[0,1]
	v_pk_add_f32 v[126:127], v[126:127], v[130:131] op_sel_hi:[1,0] neg_lo:[0,1] neg_hi:[0,1]
	v_mov_b32_e32 v130, v124
	v_mov_b32_e32 v131, v120
	v_pk_mul_f32 v[212:213], v[212:213], v[212:213]
	v_add_f32_e32 v133, v187, v133
	v_pk_fma_f32 v[210:211], v[214:215], v[214:215], v[210:211]
	v_pk_fma_f32 v[130:131], v[130:131], v[130:131], v[212:213]
	v_mov_b32_e32 v212, v126
	v_mov_b32_e32 v213, v122
	v_add_f32_e32 v132, v133, v132
	v_mov_b32_e32 v214, v127
	v_mov_b32_e32 v215, v123
	v_pk_fma_f32 v[130:131], v[212:213], v[212:213], v[130:131]
	v_add_f32_e32 v132, v211, v132
	v_pk_fma_f32 v[130:131], v[214:215], v[214:215], v[130:131]
	v_add_f32_e32 v132, v210, v132
	v_add_f32_e32 v131, v131, v132
	v_add_f32_e32 v130, v130, v131
	ds_bpermute_b32 v131, v204, v130
	s_waitcnt lgkmcnt(0)
	v_add_f32_e32 v130, v130, v131
	ds_bpermute_b32 v131, v205, v130
	s_waitcnt lgkmcnt(0)
	v_add_f32_e32 v130, v130, v131
	ds_bpermute_b32 v131, v206, v130
	s_waitcnt lgkmcnt(0)
	v_add_f32_e32 v130, v130, v131
	ds_bpermute_b32 v131, v201, v130
	s_waitcnt lgkmcnt(0)
	v_add_f32_e32 v130, v130, v131
	ds_bpermute_b32 v131, v202, v130
	s_waitcnt lgkmcnt(0)
	v_add_f32_e32 v130, v130, v131
	ds_bpermute_b32 v131, v203, v130
	s_waitcnt lgkmcnt(0)
	v_add_f32_e32 v130, v130, v131
	v_fmamk_f32 v130, v130, 0x3a000000, v208
	v_mul_f32_e32 v131, 0x4b800000, v130
	v_cmp_gt_f32_e32 vcc, s57, v130
	s_nop 1
	v_cndmask_b32_e32 v130, v130, v131, vcc
	v_rsq_f32_e32 v130, v130
	s_nop 0
	v_mul_f32_e32 v131, 0x45800000, v130
	v_cndmask_b32_e32 v130, v130, v131, vcc
	v_pk_mul_f32 v[64:65], v[64:65], v[130:131] op_sel_hi:[1,0]
	v_pk_mul_f32 v[66:67], v[66:67], v[130:131] op_sel_hi:[1,0]
	v_pk_fma_f32 v[64:65], v[0:1], v[64:65], v[8:9]
	v_pk_fma_f32 v[66:67], v[2:3], v[66:67], v[10:11]
	global_store_dwordx4 v[128:129], v[64:67], off nt
	s_nop 1
	v_pk_mul_f32 v[64:65], v[68:69], v[130:131] op_sel_hi:[1,0]
	v_pk_mul_f32 v[66:67], v[70:71], v[130:131] op_sel_hi:[1,0]
	v_pk_fma_f32 v[64:65], v[4:5], v[64:65], v[12:13]
	v_pk_fma_f32 v[66:67], v[6:7], v[66:67], v[14:15]
	global_store_dwordx4 v[128:129], v[64:67], off offset:1024 nt
	v_add_co_u32_e32 v68, vcc, s41, v128
	s_nop 0
	v_pk_mul_f32 v[64:65], v[76:77], v[130:131] op_sel_hi:[1,0]
	v_pk_mul_f32 v[66:67], v[78:79], v[130:131] op_sel_hi:[1,0]
	v_pk_fma_f32 v[64:65], v[16:17], v[64:65], v[24:25]
	v_pk_fma_f32 v[66:67], v[18:19], v[66:67], v[26:27]
	global_store_dwordx4 v[128:129], v[64:67], off offset:2048 nt
	v_addc_co_u32_e32 v69, vcc, 0, v129, vcc
	s_nop 0
	v_pk_mul_f32 v[64:65], v[80:81], v[130:131] op_sel_hi:[1,0]
	v_pk_mul_f32 v[66:67], v[82:83], v[130:131] op_sel_hi:[1,0]
	v_pk_fma_f32 v[64:65], v[20:21], v[64:65], v[28:29]
	v_pk_fma_f32 v[66:67], v[22:23], v[66:67], v[30:31]
	global_store_dwordx4 v[128:129], v[64:67], off offset:3072 nt
	s_waitcnt vmcnt(11)
	v_mov_b64_e32 v[70:71], v[74:75]
	s_waitcnt vmcnt(10)
	v_mov_b64_e32 v[76:77], v[84:85]
	v_pk_mul_f32 v[64:65], v[104:105], v[130:131] op_sel_hi:[1,0]
	v_pk_mul_f32 v[66:67], v[106:107], v[130:131] op_sel_hi:[1,0]
	v_pk_fma_f32 v[64:65], v[32:33], v[64:65], v[36:37]
	v_pk_fma_f32 v[66:67], v[34:35], v[66:67], v[38:39]
	global_store_dwordx4 v[68:69], v[64:67], off nt
	v_mov_b64_e32 v[78:79], v[86:87]
	s_waitcnt vmcnt(9)
	v_mov_b64_e32 v[80:81], v[92:93]
	v_pk_mul_f32 v[64:65], v[112:113], v[130:131] op_sel_hi:[1,0]
	v_pk_mul_f32 v[66:67], v[114:115], v[130:131] op_sel_hi:[1,0]
	v_pk_fma_f32 v[64:65], v[40:41], v[64:65], v[44:45]
	v_pk_fma_f32 v[66:67], v[42:43], v[66:67], v[46:47]
	global_store_dwordx4 v[68:69], v[64:67], off offset:1024 nt
	v_mov_b64_e32 v[82:83], v[94:95]
	s_waitcnt vmcnt(9)
	v_mov_b64_e32 v[104:105], v[96:97]
	v_pk_mul_f32 v[64:65], v[120:121], v[130:131] op_sel_hi:[1,0]
	v_pk_mul_f32 v[66:67], v[122:123], v[130:131] op_sel_hi:[1,0]
	v_pk_fma_f32 v[64:65], v[48:49], v[64:65], v[52:53]
	v_pk_fma_f32 v[66:67], v[50:51], v[66:67], v[54:55]
	global_store_dwordx4 v[68:69], v[64:67], off offset:2048 nt
	v_mov_b64_e32 v[106:107], v[98:99]
	s_waitcnt vmcnt(9)
	v_mov_b64_e32 v[112:113], v[100:101]
	v_pk_mul_f32 v[64:65], v[124:125], v[130:131] op_sel_hi:[1,0]
	v_pk_mul_f32 v[66:67], v[126:127], v[130:131] op_sel_hi:[1,0]
	v_pk_fma_f32 v[64:65], v[56:57], v[64:65], v[60:61]
	v_pk_fma_f32 v[66:67], v[58:59], v[66:67], v[62:63]
	global_store_dwordx4 v[68:69], v[64:67], off offset:3072 nt
	v_mov_b64_e32 v[68:69], v[72:73]
	v_mov_b64_e32 v[114:115], v[102:103]
	v_mov_b64_e32 v[64:65], v[88:89]
	v_mov_b64_e32 v[66:67], v[90:91]
	s_waitcnt vmcnt(9)
	v_mov_b64_e32 v[120:121], v[108:109]
	v_mov_b64_e32 v[122:123], v[110:111]
	s_waitcnt vmcnt(8)
	v_mov_b64_e32 v[124:125], v[116:117]
	v_mov_b64_e32 v[126:127], v[118:119]
	s_cbranch_scc1 .LBB0_921
.LBB0_940:
	v_add_u32_e32 v72, s0, v207
	v_ashrrev_i32_e32 v73, 31, v72
	v_lshlrev_b64 v[72:73], 13, v[72:73]
	v_lshl_add_u64 v[128:129], s[78:79], 0, v[72:73]
	s_cmp_eq_u32 s0, 15
	v_lshlrev_b32_e32 v138, 2, v136
	s_waitcnt vmcnt(19)
	v_mov_b64_e32 v[88:89], v[64:65]
	v_mov_b64_e32 v[90:91], v[66:67]
	s_waitcnt vmcnt(18)
	v_mov_b64_e32 v[72:73], v[68:69]
	v_mov_b64_e32 v[74:75], v[70:71]
	s_waitcnt vmcnt(13)
	v_mov_b64_e32 v[84:85], v[76:77]
	v_mov_b64_e32 v[86:87], v[78:79]
	s_waitcnt vmcnt(12)
	v_mov_b64_e32 v[92:93], v[80:81]
	v_mov_b64_e32 v[94:95], v[82:83]
	s_waitcnt vmcnt(7)
	v_mov_b64_e32 v[96:97], v[104:105]
	v_mov_b64_e32 v[98:99], v[106:107]
	s_waitcnt vmcnt(6)
	v_mov_b64_e32 v[100:101], v[112:113]
	v_mov_b64_e32 v[102:103], v[114:115]
	s_waitcnt vmcnt(1)
	v_mov_b64_e32 v[108:109], v[120:121]
	v_mov_b64_e32 v[110:111], v[122:123]
	s_waitcnt vmcnt(0)
	v_mov_b64_e32 v[116:117], v[124:125]
	v_mov_b64_e32 v[118:119], v[126:127]
	s_cbranch_scc1 .LBB0_939
	v_lshl_add_u64 v[96:97], v[128:129], 0, v[138:139]
	v_add_co_u32_e32 v88, vcc, 0x2000, v96
	v_lshl_add_u64 v[92:93], v[96:97], 0, s[76:77]
	s_nop 0
	v_addc_co_u32_e32 v89, vcc, 0, v97, vcc
	v_add_co_u32_e32 v116, vcc, s55, v96
	global_load_dwordx4 v[72:75], v[92:93], off offset:1024 nt
	global_load_dwordx4 v[84:87], v[92:93], off offset:2048 nt
	s_nop 0
	global_load_dwordx4 v[88:91], v[88:89], off nt
	s_nop 0
	global_load_dwordx4 v[92:95], v[92:93], off offset:3072 nt
	v_addc_co_u32_e32 v117, vcc, 0, v97, vcc
	global_load_dwordx4 v[96:99], v[116:117], off nt
	global_load_dwordx4 v[100:103], v[116:117], off offset:1024 nt
	global_load_dwordx4 v[108:111], v[116:117], off offset:2048 nt
	s_nop 0
	global_load_dwordx4 v[116:119], v[116:117], off offset:3072 nt
	s_branch .LBB0_939
